# final-norm rows: gain chunks loaded once per trip instead of behind vmcnt(0) before every store (lever 2, store-ladder de-serialisation), on top of v75
# speedup vs baseline: 1.0013x; 1.0011x over previous
.LBB0_3064:
	global_load_dwordx2 v[20:21], v[16:17], off
	global_load_dwordx2 v[22:23], v[16:17], off offset:512
	global_load_dwordx2 v[24:25], v[16:17], off offset:1024
	global_load_dwordx2 v[26:27], v[16:17], off offset:1536
	global_load_dwordx2 v[72:73], v[16:17], off offset:2048
	global_load_dwordx2 v[74:75], v[16:17], off offset:3584
	global_load_dwordx2 v[76:77], v[16:17], off offset:3072
	global_load_dwordx2 v[78:79], v[16:17], off offset:2560
	global_load_dwordx4 v[68:71], v[2:3], off
	s_add_i32 s13, s16, s0
	s_add_i32 s14, s1, s0
	s_add_i32 s12, s3, s0
	s_min_i32 s20, s13, 0x1fff
	s_min_i32 s22, s14, 0x1fff
	s_min_i32 s24, s12, 0x1fff
	s_ashr_i32 s21, s20, 31
	s_ashr_i32 s23, s22, 31
	s_ashr_i32 s25, s24, 31
	s_lshl_b64 s[20:21], s[20:21], 12
	s_lshl_b64 s[22:23], s[22:23], 12
	s_lshl_b64 s[24:25], s[24:25], 12
	v_lshl_add_u64 v[18:19], v[4:5], 0, s[20:21]
	v_lshl_add_u64 v[80:81], v[4:5], 0, s[22:23]
	v_lshl_add_u64 v[82:83], v[4:5], 0, s[24:25]
	global_load_dwordx2 v[64:65], v[18:19], off
	global_load_dwordx2 v[62:63], v[18:19], off offset:512
	global_load_dwordx2 v[60:61], v[18:19], off offset:1024
	global_load_dwordx2 v[58:59], v[18:19], off offset:1536
	global_load_dwordx2 v[56:57], v[18:19], off offset:2048
	global_load_dwordx2 v[54:55], v[18:19], off offset:2560
	global_load_dwordx2 v[52:53], v[18:19], off offset:3072
	global_load_dwordx2 v[50:51], v[18:19], off offset:3584
	global_load_dwordx2 v[48:49], v[80:81], off
	global_load_dwordx2 v[46:47], v[80:81], off offset:512
	global_load_dwordx2 v[44:45], v[80:81], off offset:1024
	global_load_dwordx2 v[42:43], v[80:81], off offset:1536
	global_load_dwordx2 v[40:41], v[80:81], off offset:2048
	global_load_dwordx2 v[38:39], v[80:81], off offset:2560
	global_load_dwordx2 v[36:37], v[80:81], off offset:3072
	global_load_dwordx2 v[34:35], v[80:81], off offset:3584
	global_load_dwordx2 v[32:33], v[82:83], off
	global_load_dwordx2 v[30:31], v[82:83], off offset:512
	global_load_dwordx2 v[28:29], v[82:83], off offset:1024
	global_load_dwordx2 v[18:19], v[82:83], off offset:1536
	v_lshl_add_u64 v[106:107], s[4:5], 0, v[0:1]
	global_load_dwordx4 v[120:123], v[2:3], off
	global_load_dwordx4 v[124:127], v[2:3], off offset:1024
	global_load_dwordx4 v[128:131], v[2:3], off offset:2048
	global_load_dwordx4 v[132:135], v[2:3], off offset:3072
	global_load_dwordx4 v[136:139], v[6:7], off
	global_load_dwordx4 v[140:143], v[8:9], off
	global_load_dwordx4 v[144:147], v[10:11], off
	global_load_dwordx4 v[148:151], v[12:13], off
	s_cmpk_gt_i32 s13, 0x1fff
	s_waitcnt vmcnt(28)
	v_and_b32_e32 v81, 0xffff0000, v20
	v_and_b32_e32 v85, 0xffff0000, v21
	s_waitcnt vmcnt(27)
	v_and_b32_e32 v87, 0xffff0000, v22
	v_and_b32_e32 v89, 0xffff0000, v23
	v_lshlrev_b32_e32 v80, 16, v20
	v_lshlrev_b32_e32 v84, 16, v21
	v_lshlrev_b32_e32 v86, 16, v22
	v_lshlrev_b32_e32 v88, 16, v23
	s_waitcnt vmcnt(26)
	v_and_b32_e32 v91, 0xffff0000, v24
	v_and_b32_e32 v93, 0xffff0000, v25
	v_mul_f32_e32 v20, v81, v81
	v_mul_f32_e32 v21, v85, v85
	v_mul_f32_e32 v22, v87, v87
	v_mul_f32_e32 v23, v89, v89
	v_lshlrev_b32_e32 v90, 16, v24
	v_lshlrev_b32_e32 v92, 16, v25
	v_mul_f32_e32 v24, v91, v91
	v_mul_f32_e32 v25, v93, v93
	v_fmac_f32_e32 v20, v80, v80
	v_fmac_f32_e32 v21, v84, v84
	v_fmac_f32_e32 v22, v86, v86
	v_fmac_f32_e32 v23, v88, v88
	s_waitcnt vmcnt(25)
	v_and_b32_e32 v95, 0xffff0000, v26
	v_and_b32_e32 v97, 0xffff0000, v27
	v_fmac_f32_e32 v24, v90, v90
	v_fmac_f32_e32 v25, v92, v92
	v_add_f32_e32 v20, v20, v21
	v_add_f32_e32 v21, v22, v23
	v_lshlrev_b32_e32 v94, 16, v26
	v_lshlrev_b32_e32 v96, 16, v27
	s_waitcnt vmcnt(24)
	v_lshlrev_b32_e32 v98, 16, v72
	v_and_b32_e32 v99, 0xffff0000, v72
	v_lshlrev_b32_e32 v72, 16, v73
	v_and_b32_e32 v73, 0xffff0000, v73
	v_mul_f32_e32 v26, v95, v95
	v_mul_f32_e32 v27, v97, v97
	v_add_f32_e32 v22, v24, v25
	v_add_f32_e32 v20, v21, v20
	v_fmac_f32_e32 v26, v94, v94
	v_fmac_f32_e32 v27, v96, v96
	v_add_f32_e32 v20, v22, v20
	v_mul_f32_e32 v21, v99, v99
	v_mul_f32_e32 v22, v73, v73
	v_add_f32_e32 v23, v26, v27
	v_fmac_f32_e32 v21, v98, v98
	v_fmac_f32_e32 v22, v72, v72
	v_add_f32_e32 v20, v23, v20
	v_add_f32_e32 v21, v21, v22
	s_waitcnt vmcnt(21)
	v_lshlrev_b32_e32 v100, 16, v78
	v_and_b32_e32 v101, 0xffff0000, v78
	v_lshlrev_b32_e32 v78, 16, v79
	v_and_b32_e32 v79, 0xffff0000, v79
	v_add_f32_e32 v20, v21, v20
	v_mul_f32_e32 v21, v101, v101
	v_mul_f32_e32 v22, v79, v79
	v_fmac_f32_e32 v21, v100, v100
	v_fmac_f32_e32 v22, v78, v78
	v_add_f32_e32 v21, v21, v22
	v_lshlrev_b32_e32 v102, 16, v76
	v_and_b32_e32 v103, 0xffff0000, v76
	v_lshlrev_b32_e32 v76, 16, v77
	v_and_b32_e32 v77, 0xffff0000, v77
	v_add_f32_e32 v20, v21, v20
	v_mul_f32_e32 v21, v103, v103
	v_mul_f32_e32 v22, v77, v77
	v_fmac_f32_e32 v21, v102, v102
	v_fmac_f32_e32 v22, v76, v76
	v_add_f32_e32 v21, v21, v22
	v_lshlrev_b32_e32 v104, 16, v74
	v_and_b32_e32 v105, 0xffff0000, v74
	v_lshlrev_b32_e32 v74, 16, v75
	v_and_b32_e32 v75, 0xffff0000, v75
	v_add_f32_e32 v20, v21, v20
	v_mul_f32_e32 v21, v105, v105
	v_mul_f32_e32 v22, v75, v75
	v_fmac_f32_e32 v21, v104, v104
	v_fmac_f32_e32 v22, v74, v74
	v_add_f32_e32 v21, v21, v22
	v_add_f32_e32 v20, v21, v20
	s_nop 1
	v_add_f32_dpp v20, v20, v20 quad_perm:[1,0,3,2] row_mask:0xf bank_mask:0xf bound_ctrl:1
	s_nop 1
	v_add_f32_dpp v20, v20, v20 quad_perm:[2,3,0,1] row_mask:0xf bank_mask:0xf bound_ctrl:1
	s_nop 1
	v_add_f32_dpp v20, v20, v20 row_half_mirror row_mask:0xf bank_mask:0xf bound_ctrl:1
	s_nop 1
	v_add_f32_dpp v20, v20, v20 row_mirror row_mask:0xf bank_mask:0xf bound_ctrl:1
	v_mov_b32_e32 v21, v20
	s_nop 1
	v_permlane16_swap_b32_e32 v20, v21
	v_add_f32_e32 v20, v20, v21
	v_mov_b32_e32 v21, v20
	s_nop 1
	v_permlane32_swap_b32_e32 v20, v21
	v_add_f32_e32 v20, v20, v21
	v_fmamk_f32 v20, v20, 0x3a000000, v66
	v_mul_f32_e32 v21, 0x4b800000, v20
	v_cmp_gt_f32_e32 vcc, s17, v20
	s_nop 1
	v_cndmask_b32_e32 v20, v20, v21, vcc
	v_rsq_f32_e32 v67, v20
	global_load_dwordx2 v[26:27], v[82:83], off offset:2048
	global_load_dwordx2 v[24:25], v[82:83], off offset:2560
	global_load_dwordx2 v[22:23], v[82:83], off offset:3072
	global_load_dwordx2 v[20:21], v[82:83], off offset:3584
	v_mul_f32_e32 v82, 0x45800000, v67
	v_cndmask_b32_e32 v82, v67, v82, vcc
	v_pk_mul_f32 v[80:81], v[80:81], v[82:83] op_sel_hi:[1,0]
	v_pk_mul_f32 v[84:85], v[84:85], v[82:83] op_sel_hi:[1,0]
	s_waitcnt vmcnt(0)
	v_pk_mul_f32 v[68:69], v[68:69], v[80:81]
	v_pk_mul_f32 v[70:71], v[70:71], v[84:85]
	global_store_dwordx4 v[106:107], v[68:71], off
	s_nop 1
	v_mov_b64_e32 v[68:69], v[124:125]
	v_mov_b64_e32 v[70:71], v[126:127]
	v_pk_mul_f32 v[80:81], v[88:89], v[82:83] op_sel_hi:[1,0]
	v_pk_mul_f32 v[84:85], v[86:87], v[82:83] op_sel_hi:[1,0]
	v_pk_mul_f32 v[72:73], v[72:73], v[82:83] op_sel_hi:[1,0]
	s_nop 0
	v_pk_mul_f32 v[68:69], v[68:69], v[84:85]
	v_pk_mul_f32 v[70:71], v[70:71], v[80:81]
	global_store_dwordx4 v[106:107], v[68:71], off offset:1024
	s_nop 1
	v_mov_b64_e32 v[68:69], v[128:129]
	v_mov_b64_e32 v[70:71], v[130:131]
	v_pk_mul_f32 v[80:81], v[92:93], v[82:83] op_sel_hi:[1,0]
	v_pk_mul_f32 v[84:85], v[90:91], v[82:83] op_sel_hi:[1,0]
	s_nop 0
	v_pk_mul_f32 v[70:71], v[70:71], v[80:81]
	v_pk_mul_f32 v[68:69], v[68:69], v[84:85]
	global_store_dwordx4 v[106:107], v[68:71], off offset:2048
	s_nop 1
	v_mov_b64_e32 v[68:69], v[132:133]
	v_mov_b64_e32 v[70:71], v[134:135]
	v_pk_mul_f32 v[80:81], v[96:97], v[82:83] op_sel_hi:[1,0]
	v_pk_mul_f32 v[84:85], v[94:95], v[82:83] op_sel_hi:[1,0]
	s_nop 0
	v_pk_mul_f32 v[70:71], v[70:71], v[80:81]
	v_pk_mul_f32 v[68:69], v[68:69], v[84:85]
	global_store_dwordx4 v[106:107], v[68:71], off offset:3072
	s_nop 1
	v_mov_b64_e32 v[68:69], v[136:137]
	v_mov_b64_e32 v[70:71], v[138:139]
	v_add_co_u32_e32 v80, vcc, s18, v106
	v_pk_mul_f32 v[84:85], v[98:99], v[82:83] op_sel_hi:[1,0]
	s_nop 0
	v_addc_co_u32_e32 v81, vcc, 0, v107, vcc
	s_nop 0
	v_pk_mul_f32 v[68:69], v[68:69], v[84:85]
	v_pk_mul_f32 v[70:71], v[70:71], v[72:73]
	global_store_dwordx4 v[80:81], v[68:71], off
	s_nop 1
	v_mov_b64_e32 v[68:69], v[140:141]
	v_mov_b64_e32 v[70:71], v[142:143]
	v_pk_mul_f32 v[72:73], v[78:79], v[82:83] op_sel_hi:[1,0]
	v_pk_mul_f32 v[78:79], v[100:101], v[82:83] op_sel_hi:[1,0]
	s_nop 0
	v_pk_mul_f32 v[70:71], v[70:71], v[72:73]
	v_pk_mul_f32 v[68:69], v[68:69], v[78:79]
	global_store_dwordx4 v[80:81], v[68:71], off offset:1024
	s_nop 1
	v_mov_b64_e32 v[68:69], v[144:145]
	v_mov_b64_e32 v[70:71], v[146:147]
	v_pk_mul_f32 v[72:73], v[76:77], v[82:83] op_sel_hi:[1,0]
	v_pk_mul_f32 v[76:77], v[102:103], v[82:83] op_sel_hi:[1,0]
	s_nop 0
	v_pk_mul_f32 v[70:71], v[72:73], v[70:71]
	v_pk_mul_f32 v[68:69], v[76:77], v[68:69]
	global_store_dwordx4 v[80:81], v[68:71], off offset:2048
	s_nop 1
	v_mov_b64_e32 v[68:69], v[148:149]
	v_mov_b64_e32 v[70:71], v[150:151]
	v_pk_mul_f32 v[72:73], v[74:75], v[82:83] op_sel_hi:[1,0]
	v_pk_mul_f32 v[74:75], v[104:105], v[82:83] op_sel_hi:[1,0]
	s_nop 0
	v_pk_mul_f32 v[70:71], v[72:73], v[70:71]
	v_pk_mul_f32 v[68:69], v[74:75], v[68:69]
	global_store_dwordx4 v[80:81], v[68:71], off offset:3072
	s_cbranch_scc1 .LBB0_3067
	s_nop 0
	v_lshlrev_b32_e32 v68, 16, v64
	v_and_b32_e32 v69, 0xffff0000, v64
	v_lshlrev_b32_e32 v64, 16, v65
	v_and_b32_e32 v65, 0xffff0000, v65
	v_mul_f32_e32 v67, v69, v69
	v_mul_f32_e32 v70, v65, v65
	v_fmac_f32_e32 v67, v68, v68
	v_fmac_f32_e32 v70, v64, v64
	v_and_b32_e32 v71, 0xffff0000, v62
	v_and_b32_e32 v73, 0xffff0000, v63
	v_add_f32_e32 v67, v67, v70
	v_lshlrev_b32_e32 v70, 16, v62
	v_lshlrev_b32_e32 v72, 16, v63
	v_mul_f32_e32 v62, v71, v71
	v_mul_f32_e32 v63, v73, v73
	v_fmac_f32_e32 v62, v70, v70
	v_fmac_f32_e32 v63, v72, v72
	v_add_f32_e32 v62, v62, v63
	v_add_f32_e32 v67, v67, v62
	v_lshlrev_b32_e32 v74, 16, v60
	v_and_b32_e32 v75, 0xffff0000, v60
	v_lshlrev_b32_e32 v76, 16, v61
	v_and_b32_e32 v77, 0xffff0000, v61
	s_nop 1
	v_mov_b64_e32 v[60:61], v[120:121]
	v_mov_b64_e32 v[62:63], v[122:123]
	v_mul_f32_e32 v78, v75, v75
	v_mul_f32_e32 v79, v77, v77
	v_fmac_f32_e32 v78, v74, v74
	v_fmac_f32_e32 v79, v76, v76
	v_add_f32_e32 v78, v78, v79
	v_add_f32_e32 v67, v67, v78
	v_lshlrev_b32_e32 v78, 16, v58
	v_and_b32_e32 v79, 0xffff0000, v58
	v_lshlrev_b32_e32 v58, 16, v59
	v_and_b32_e32 v59, 0xffff0000, v59
	v_mul_f32_e32 v80, v79, v79
	v_mul_f32_e32 v81, v59, v59
	v_fmac_f32_e32 v80, v78, v78
	v_fmac_f32_e32 v81, v58, v58
	v_add_f32_e32 v80, v80, v81
	v_add_f32_e32 v67, v67, v80
	v_lshlrev_b32_e32 v80, 16, v56
	v_and_b32_e32 v81, 0xffff0000, v56
	v_lshlrev_b32_e32 v56, 16, v57
	v_and_b32_e32 v57, 0xffff0000, v57
	v_mul_f32_e32 v82, v81, v81
	v_mul_f32_e32 v83, v57, v57
	v_fmac_f32_e32 v82, v80, v80
	v_fmac_f32_e32 v83, v56, v56
	v_add_f32_e32 v82, v82, v83
	v_add_f32_e32 v67, v67, v82
	v_lshlrev_b32_e32 v82, 16, v54
	v_and_b32_e32 v83, 0xffff0000, v54
	v_lshlrev_b32_e32 v54, 16, v55
	v_and_b32_e32 v55, 0xffff0000, v55
	v_mul_f32_e32 v84, v83, v83
	v_mul_f32_e32 v85, v55, v55
	v_fmac_f32_e32 v84, v82, v82
	v_fmac_f32_e32 v85, v54, v54
	v_add_f32_e32 v84, v84, v85
	v_and_b32_e32 v85, 0xffff0000, v52
	v_and_b32_e32 v87, 0xffff0000, v53
	v_add_f32_e32 v67, v67, v84
	v_lshlrev_b32_e32 v84, 16, v52
	v_lshlrev_b32_e32 v86, 16, v53
	v_mul_f32_e32 v52, v85, v85
	v_mul_f32_e32 v53, v87, v87
	v_and_b32_e32 v89, 0xffff0000, v50
	v_and_b32_e32 v91, 0xffff0000, v51
	v_fmac_f32_e32 v52, v84, v84
	v_fmac_f32_e32 v53, v86, v86
	v_lshlrev_b32_e32 v88, 16, v50
	v_lshlrev_b32_e32 v90, 16, v51
	v_mul_f32_e32 v50, v89, v89
	v_mul_f32_e32 v51, v91, v91
	v_add_f32_e32 v52, v52, v53
	v_fmac_f32_e32 v50, v88, v88
	v_fmac_f32_e32 v51, v90, v90
	v_add_f32_e32 v52, v67, v52
	v_add_f32_e32 v50, v50, v51
	v_add_f32_e32 v50, v52, v50
	v_lshl_add_u64 v[94:95], s[8:9], 0, v[0:1]
	s_nop 0
	v_add_f32_dpp v50, v50, v50 quad_perm:[1,0,3,2] row_mask:0xf bank_mask:0xf bound_ctrl:1
	s_nop 1
	v_add_f32_dpp v50, v50, v50 quad_perm:[2,3,0,1] row_mask:0xf bank_mask:0xf bound_ctrl:1
	s_nop 1
	v_add_f32_dpp v50, v50, v50 row_half_mirror row_mask:0xf bank_mask:0xf bound_ctrl:1
	s_nop 1
	v_add_f32_dpp v50, v50, v50 row_mirror row_mask:0xf bank_mask:0xf bound_ctrl:1
	v_mov_b32_e32 v51, v50
	s_nop 1
	v_permlane16_swap_b32_e32 v50, v51
	v_add_f32_e32 v50, v50, v51
	v_mov_b32_e32 v51, v50
	s_nop 1
	v_permlane32_swap_b32_e32 v50, v51
	v_add_f32_e32 v50, v50, v51
	v_fmamk_f32 v50, v50, 0x3a000000, v66
	v_mul_f32_e32 v51, 0x4b800000, v50
	v_cmp_gt_f32_e32 vcc, s17, v50
	s_nop 1
	v_cndmask_b32_e32 v50, v50, v51, vcc
	v_rsq_f32_e32 v50, v50
	s_nop 0
	v_mul_f32_e32 v51, 0x45800000, v50
	v_cndmask_b32_e32 v92, v50, v51, vcc
	v_pk_mul_f32 v[50:51], v[68:69], v[92:93] op_sel_hi:[1,0]
	v_pk_mul_f32 v[52:53], v[64:65], v[92:93] op_sel_hi:[1,0]
	s_nop 0
	v_pk_mul_f32 v[50:51], v[60:61], v[50:51]
	v_pk_mul_f32 v[52:53], v[62:63], v[52:53]
	global_store_dwordx4 v[94:95], v[50:53], off
	s_nop 1
	v_mov_b64_e32 v[50:51], v[124:125]
	v_mov_b64_e32 v[52:53], v[126:127]
	v_pk_mul_f32 v[60:61], v[72:73], v[92:93] op_sel_hi:[1,0]
	v_pk_mul_f32 v[62:63], v[70:71], v[92:93] op_sel_hi:[1,0]
	v_pk_mul_f32 v[58:59], v[58:59], v[92:93] op_sel_hi:[1,0]
	v_pk_mul_f32 v[56:57], v[56:57], v[92:93] op_sel_hi:[1,0]
	v_pk_mul_f32 v[54:55], v[54:55], v[92:93] op_sel_hi:[1,0]
	s_nop 0
	v_pk_mul_f32 v[50:51], v[50:51], v[62:63]
	v_pk_mul_f32 v[52:53], v[52:53], v[60:61]
	global_store_dwordx4 v[94:95], v[50:53], off offset:1024
	s_nop 1
	v_mov_b64_e32 v[50:51], v[128:129]
	v_mov_b64_e32 v[52:53], v[130:131]
	v_pk_mul_f32 v[60:61], v[76:77], v[92:93] op_sel_hi:[1,0]
	v_pk_mul_f32 v[62:63], v[74:75], v[92:93] op_sel_hi:[1,0]
	s_nop 0
	v_pk_mul_f32 v[52:53], v[52:53], v[60:61]
	v_pk_mul_f32 v[50:51], v[50:51], v[62:63]
	global_store_dwordx4 v[94:95], v[50:53], off offset:2048
	s_nop 1
	v_mov_b64_e32 v[50:51], v[132:133]
	v_mov_b64_e32 v[52:53], v[134:135]
	v_pk_mul_f32 v[60:61], v[78:79], v[92:93] op_sel_hi:[1,0]
	s_nop 0
	v_pk_mul_f32 v[52:53], v[52:53], v[58:59]
	v_pk_mul_f32 v[50:51], v[50:51], v[60:61]
	global_store_dwordx4 v[94:95], v[50:53], off offset:3072
	s_nop 1
	v_mov_b64_e32 v[50:51], v[136:137]
	v_mov_b64_e32 v[52:53], v[138:139]
	v_add_co_u32_e32 v58, vcc, s18, v94
	v_pk_mul_f32 v[60:61], v[80:81], v[92:93] op_sel_hi:[1,0]
	s_nop 0
	v_addc_co_u32_e32 v59, vcc, 0, v95, vcc
	s_nop 0
	v_pk_mul_f32 v[50:51], v[50:51], v[60:61]
	v_pk_mul_f32 v[52:53], v[52:53], v[56:57]
	global_store_dwordx4 v[58:59], v[50:53], off
	s_nop 1
	v_mov_b64_e32 v[50:51], v[140:141]
	v_mov_b64_e32 v[52:53], v[142:143]
	v_pk_mul_f32 v[56:57], v[82:83], v[92:93] op_sel_hi:[1,0]
	s_nop 0
	v_pk_mul_f32 v[52:53], v[52:53], v[54:55]
	v_pk_mul_f32 v[50:51], v[50:51], v[56:57]
	global_store_dwordx4 v[58:59], v[50:53], off offset:1024
	s_nop 1
	v_mov_b64_e32 v[50:51], v[144:145]
	v_mov_b64_e32 v[52:53], v[146:147]
	v_pk_mul_f32 v[54:55], v[86:87], v[92:93] op_sel_hi:[1,0]
	v_pk_mul_f32 v[56:57], v[84:85], v[92:93] op_sel_hi:[1,0]
	s_nop 0
	v_pk_mul_f32 v[52:53], v[54:55], v[52:53]
	v_pk_mul_f32 v[50:51], v[56:57], v[50:51]
	global_store_dwordx4 v[58:59], v[50:53], off offset:2048
	s_nop 1
	v_mov_b64_e32 v[50:51], v[148:149]
	v_mov_b64_e32 v[52:53], v[150:151]
	v_pk_mul_f32 v[54:55], v[90:91], v[92:93] op_sel_hi:[1,0]
	v_pk_mul_f32 v[56:57], v[88:89], v[92:93] op_sel_hi:[1,0]
	s_nop 0
	v_pk_mul_f32 v[52:53], v[54:55], v[52:53]
	v_pk_mul_f32 v[50:51], v[56:57], v[50:51]
	global_store_dwordx4 v[58:59], v[50:53], off offset:3072
	s_cmpk_gt_i32 s14, 0x1fff
	s_cbranch_scc0 .LBB0_3068

.LBB0_3068:
	v_lshlrev_b32_e32 v50, 16, v48
	v_and_b32_e32 v51, 0xffff0000, v48
	v_lshlrev_b32_e32 v48, 16, v49
	v_and_b32_e32 v49, 0xffff0000, v49
	v_mul_f32_e32 v52, v51, v51
	v_mul_f32_e32 v53, v49, v49
	v_fmac_f32_e32 v52, v50, v50
	v_fmac_f32_e32 v53, v48, v48
	v_add_f32_e32 v56, v52, v53
	v_and_b32_e32 v53, 0xffff0000, v46
	v_and_b32_e32 v55, 0xffff0000, v47
	v_lshlrev_b32_e32 v52, 16, v46
	v_lshlrev_b32_e32 v54, 16, v47
	v_mul_f32_e32 v46, v53, v53
	v_mul_f32_e32 v47, v55, v55
	v_fmac_f32_e32 v46, v52, v52
	v_fmac_f32_e32 v47, v54, v54
	v_add_f32_e32 v46, v46, v47
	v_add_f32_e32 v60, v56, v46
	v_lshlrev_b32_e32 v56, 16, v44
	v_and_b32_e32 v57, 0xffff0000, v44
	v_lshlrev_b32_e32 v58, 16, v45
	v_and_b32_e32 v59, 0xffff0000, v45
	s_nop 1
	v_mov_b64_e32 v[44:45], v[120:121]
	v_mov_b64_e32 v[46:47], v[122:123]
	v_mul_f32_e32 v61, v57, v57
	v_mul_f32_e32 v62, v59, v59
	v_fmac_f32_e32 v61, v56, v56
	v_fmac_f32_e32 v62, v58, v58
	v_add_f32_e32 v61, v61, v62
	v_add_f32_e32 v62, v60, v61
	v_lshlrev_b32_e32 v60, 16, v42
	v_and_b32_e32 v61, 0xffff0000, v42
	v_lshlrev_b32_e32 v42, 16, v43
	v_and_b32_e32 v43, 0xffff0000, v43
	v_mul_f32_e32 v63, v61, v61
	v_mul_f32_e32 v64, v43, v43
	v_fmac_f32_e32 v63, v60, v60
	v_fmac_f32_e32 v64, v42, v42
	v_add_f32_e32 v63, v63, v64
	v_add_f32_e32 v64, v62, v63
	v_lshlrev_b32_e32 v62, 16, v40
	v_and_b32_e32 v63, 0xffff0000, v40
	v_lshlrev_b32_e32 v40, 16, v41
	v_and_b32_e32 v41, 0xffff0000, v41
	v_mul_f32_e32 v65, v63, v63
	v_mul_f32_e32 v67, v41, v41
	v_fmac_f32_e32 v65, v62, v62
	v_fmac_f32_e32 v67, v40, v40
	v_add_f32_e32 v65, v65, v67
	v_add_f32_e32 v67, v64, v65
	v_lshlrev_b32_e32 v64, 16, v38
	v_and_b32_e32 v65, 0xffff0000, v38
	v_lshlrev_b32_e32 v38, 16, v39
	v_and_b32_e32 v39, 0xffff0000, v39
	v_mul_f32_e32 v68, v65, v65
	v_mul_f32_e32 v69, v39, v39
	v_fmac_f32_e32 v68, v64, v64
	v_fmac_f32_e32 v69, v38, v38
	v_add_f32_e32 v68, v68, v69
	v_and_b32_e32 v69, 0xffff0000, v36
	v_and_b32_e32 v71, 0xffff0000, v37
	v_add_f32_e32 v67, v67, v68
	v_lshlrev_b32_e32 v68, 16, v36
	v_lshlrev_b32_e32 v70, 16, v37
	v_mul_f32_e32 v36, v69, v69
	v_mul_f32_e32 v37, v71, v71
	v_and_b32_e32 v73, 0xffff0000, v34
	v_and_b32_e32 v75, 0xffff0000, v35
	v_fmac_f32_e32 v36, v68, v68
	v_fmac_f32_e32 v37, v70, v70
	v_lshlrev_b32_e32 v72, 16, v34
	v_lshlrev_b32_e32 v74, 16, v35
	v_mul_f32_e32 v34, v73, v73
	v_mul_f32_e32 v35, v75, v75
	v_add_f32_e32 v36, v36, v37
	v_fmac_f32_e32 v34, v72, v72
	v_fmac_f32_e32 v35, v74, v74
	v_add_f32_e32 v36, v67, v36
	v_add_f32_e32 v34, v34, v35
	v_add_f32_e32 v34, v36, v34
	s_ashr_i32 s15, s14, 31
	s_lshl_b64 s[14:15], s[14:15], 13
	v_add_f32_dpp v34, v34, v34 quad_perm:[1,0,3,2] row_mask:0xf bank_mask:0xf bound_ctrl:1
	v_lshl_add_u64 v[78:79], v[14:15], 0, s[14:15]
	s_nop 0
	v_add_f32_dpp v34, v34, v34 quad_perm:[2,3,0,1] row_mask:0xf bank_mask:0xf bound_ctrl:1
	s_nop 1
	v_add_f32_dpp v34, v34, v34 row_half_mirror row_mask:0xf bank_mask:0xf bound_ctrl:1
	s_nop 1
	v_add_f32_dpp v34, v34, v34 row_mirror row_mask:0xf bank_mask:0xf bound_ctrl:1
	v_mov_b32_e32 v35, v34
	s_nop 1
	v_permlane16_swap_b32_e32 v34, v35
	v_add_f32_e32 v34, v34, v35
	v_mov_b32_e32 v35, v34
	s_nop 1
	v_permlane32_swap_b32_e32 v34, v35
	v_add_f32_e32 v34, v34, v35
	v_fmamk_f32 v34, v34, 0x3a000000, v66
	v_mul_f32_e32 v35, 0x4b800000, v34
	v_cmp_gt_f32_e32 vcc, s17, v34
	s_nop 1
	v_cndmask_b32_e32 v34, v34, v35, vcc
	v_rsq_f32_e32 v34, v34
	s_nop 0
	v_mul_f32_e32 v35, 0x45800000, v34
	v_cndmask_b32_e32 v76, v34, v35, vcc
	v_pk_mul_f32 v[34:35], v[50:51], v[76:77] op_sel_hi:[1,0]
	v_pk_mul_f32 v[36:37], v[48:49], v[76:77] op_sel_hi:[1,0]
	s_nop 0
	v_pk_mul_f32 v[34:35], v[44:45], v[34:35]
	v_pk_mul_f32 v[36:37], v[46:47], v[36:37]
	global_store_dwordx4 v[78:79], v[34:37], off
	s_nop 1
	v_mov_b64_e32 v[34:35], v[124:125]
	v_mov_b64_e32 v[36:37], v[126:127]
	v_pk_mul_f32 v[44:45], v[54:55], v[76:77] op_sel_hi:[1,0]
	v_pk_mul_f32 v[46:47], v[52:53], v[76:77] op_sel_hi:[1,0]
	v_pk_mul_f32 v[42:43], v[42:43], v[76:77] op_sel_hi:[1,0]
	v_pk_mul_f32 v[40:41], v[40:41], v[76:77] op_sel_hi:[1,0]
	v_pk_mul_f32 v[38:39], v[38:39], v[76:77] op_sel_hi:[1,0]
	s_nop 0
	v_pk_mul_f32 v[34:35], v[34:35], v[46:47]
	v_pk_mul_f32 v[36:37], v[36:37], v[44:45]
	global_store_dwordx4 v[78:79], v[34:37], off offset:1024
	s_nop 1
	v_mov_b64_e32 v[34:35], v[128:129]
	v_mov_b64_e32 v[36:37], v[130:131]
	v_pk_mul_f32 v[44:45], v[58:59], v[76:77] op_sel_hi:[1,0]
	v_pk_mul_f32 v[46:47], v[56:57], v[76:77] op_sel_hi:[1,0]
	s_nop 0
	v_pk_mul_f32 v[36:37], v[36:37], v[44:45]
	v_pk_mul_f32 v[34:35], v[34:35], v[46:47]
	global_store_dwordx4 v[78:79], v[34:37], off offset:2048
	s_nop 1
	v_mov_b64_e32 v[34:35], v[132:133]
	v_mov_b64_e32 v[36:37], v[134:135]
	v_pk_mul_f32 v[44:45], v[60:61], v[76:77] op_sel_hi:[1,0]
	s_nop 0
	v_pk_mul_f32 v[36:37], v[36:37], v[42:43]
	v_pk_mul_f32 v[34:35], v[34:35], v[44:45]
	global_store_dwordx4 v[78:79], v[34:37], off offset:3072
	s_nop 1
	v_mov_b64_e32 v[34:35], v[136:137]
	v_mov_b64_e32 v[36:37], v[138:139]
	v_add_co_u32_e32 v42, vcc, s18, v78
	v_pk_mul_f32 v[44:45], v[62:63], v[76:77] op_sel_hi:[1,0]
	s_nop 0
	v_addc_co_u32_e32 v43, vcc, 0, v79, vcc
	s_nop 0
	v_pk_mul_f32 v[34:35], v[34:35], v[44:45]
	v_pk_mul_f32 v[36:37], v[36:37], v[40:41]
	global_store_dwordx4 v[42:43], v[34:37], off
	s_nop 1
	v_mov_b64_e32 v[34:35], v[140:141]
	v_mov_b64_e32 v[36:37], v[142:143]
	v_pk_mul_f32 v[40:41], v[64:65], v[76:77] op_sel_hi:[1,0]
	s_nop 0
	v_pk_mul_f32 v[36:37], v[36:37], v[38:39]
	v_pk_mul_f32 v[34:35], v[34:35], v[40:41]
	global_store_dwordx4 v[42:43], v[34:37], off offset:1024
	s_nop 1
	v_mov_b64_e32 v[34:35], v[144:145]
	v_mov_b64_e32 v[36:37], v[146:147]
	v_pk_mul_f32 v[38:39], v[70:71], v[76:77] op_sel_hi:[1,0]
	v_pk_mul_f32 v[40:41], v[68:69], v[76:77] op_sel_hi:[1,0]
	s_nop 0
	v_pk_mul_f32 v[36:37], v[38:39], v[36:37]
	v_pk_mul_f32 v[34:35], v[40:41], v[34:35]
	global_store_dwordx4 v[42:43], v[34:37], off offset:2048
	s_nop 1
	v_mov_b64_e32 v[34:35], v[148:149]
	v_mov_b64_e32 v[36:37], v[150:151]
	v_pk_mul_f32 v[38:39], v[74:75], v[76:77] op_sel_hi:[1,0]
	v_pk_mul_f32 v[40:41], v[72:73], v[76:77] op_sel_hi:[1,0]
	s_nop 0
	v_pk_mul_f32 v[36:37], v[38:39], v[36:37]
	v_pk_mul_f32 v[34:35], v[40:41], v[34:35]
	global_store_dwordx4 v[42:43], v[34:37], off offset:3072
	s_cmpk_gt_i32 s12, 0x1fff
	s_cbranch_scc1 .LBB0_3063
.LBB0_3069:
	v_lshlrev_b32_e32 v34, 16, v32
	v_and_b32_e32 v35, 0xffff0000, v32
	v_lshlrev_b32_e32 v32, 16, v33
	v_and_b32_e32 v33, 0xffff0000, v33
	v_mul_f32_e32 v36, v35, v35
	v_mul_f32_e32 v37, v33, v33
	v_fmac_f32_e32 v36, v34, v34
	v_fmac_f32_e32 v37, v32, v32
	v_add_f32_e32 v40, v36, v37
	v_and_b32_e32 v37, 0xffff0000, v30
	v_and_b32_e32 v39, 0xffff0000, v31
	v_lshlrev_b32_e32 v36, 16, v30
	v_lshlrev_b32_e32 v38, 16, v31
	v_mul_f32_e32 v30, v37, v37
	v_mul_f32_e32 v31, v39, v39
	v_fmac_f32_e32 v30, v36, v36
	v_fmac_f32_e32 v31, v38, v38
	v_add_f32_e32 v30, v30, v31
	v_add_f32_e32 v44, v40, v30
	v_lshlrev_b32_e32 v40, 16, v28
	v_and_b32_e32 v41, 0xffff0000, v28
	v_lshlrev_b32_e32 v42, 16, v29
	v_and_b32_e32 v43, 0xffff0000, v29
	s_nop 1
	v_mov_b64_e32 v[28:29], v[120:121]
	v_mov_b64_e32 v[30:31], v[122:123]
	v_mul_f32_e32 v45, v41, v41
	v_mul_f32_e32 v46, v43, v43
	v_fmac_f32_e32 v45, v40, v40
	v_fmac_f32_e32 v46, v42, v42
	v_add_f32_e32 v45, v45, v46
	v_add_f32_e32 v48, v44, v45
	v_and_b32_e32 v45, 0xffff0000, v18
	v_and_b32_e32 v47, 0xffff0000, v19
	v_lshlrev_b32_e32 v44, 16, v18
	v_lshlrev_b32_e32 v46, 16, v19
	v_mul_f32_e32 v18, v45, v45
	v_mul_f32_e32 v19, v47, v47
	v_fmac_f32_e32 v18, v44, v44
	v_fmac_f32_e32 v19, v46, v46
	v_add_f32_e32 v18, v18, v19
	v_add_f32_e32 v18, v48, v18
	v_lshlrev_b32_e32 v48, 16, v26
	v_and_b32_e32 v49, 0xffff0000, v26
	v_lshlrev_b32_e32 v26, 16, v27
	v_and_b32_e32 v27, 0xffff0000, v27
	v_mul_f32_e32 v19, v49, v49
	v_mul_f32_e32 v50, v27, v27
	v_fmac_f32_e32 v19, v48, v48
	v_fmac_f32_e32 v50, v26, v26
	v_add_f32_e32 v19, v19, v50
	v_lshlrev_b32_e32 v50, 16, v24
	v_and_b32_e32 v51, 0xffff0000, v24
	v_lshlrev_b32_e32 v24, 16, v25
	v_and_b32_e32 v25, 0xffff0000, v25
	v_add_f32_e32 v18, v18, v19
	v_mul_f32_e32 v19, v51, v51
	v_mul_f32_e32 v52, v25, v25
	v_fmac_f32_e32 v19, v50, v50
	v_fmac_f32_e32 v52, v24, v24
	v_add_f32_e32 v19, v19, v52
	v_lshlrev_b32_e32 v52, 16, v22
	v_and_b32_e32 v53, 0xffff0000, v22
	v_lshlrev_b32_e32 v22, 16, v23
	v_and_b32_e32 v23, 0xffff0000, v23
	v_add_f32_e32 v18, v18, v19
	v_mul_f32_e32 v19, v53, v53
	v_mul_f32_e32 v54, v23, v23
	v_fmac_f32_e32 v19, v52, v52
	v_fmac_f32_e32 v54, v22, v22
	v_add_f32_e32 v19, v19, v54
	v_and_b32_e32 v55, 0xffff0000, v20
	v_and_b32_e32 v57, 0xffff0000, v21
	v_add_f32_e32 v18, v18, v19
	v_lshlrev_b32_e32 v54, 16, v20
	v_lshlrev_b32_e32 v56, 16, v21
	v_mul_f32_e32 v19, v55, v55
	v_mul_f32_e32 v20, v57, v57
	v_fmac_f32_e32 v19, v54, v54
	v_fmac_f32_e32 v20, v56, v56
	v_add_f32_e32 v19, v19, v20
	v_add_f32_e32 v18, v18, v19
	s_ashr_i32 s13, s12, 31
	s_lshl_b64 s[12:13], s[12:13], 13
	v_add_f32_dpp v18, v18, v18 quad_perm:[1,0,3,2] row_mask:0xf bank_mask:0xf bound_ctrl:1
	v_lshl_add_u64 v[60:61], v[14:15], 0, s[12:13]
	s_nop 0
	v_add_f32_dpp v18, v18, v18 quad_perm:[2,3,0,1] row_mask:0xf bank_mask:0xf bound_ctrl:1
	s_nop 1
	v_add_f32_dpp v18, v18, v18 row_half_mirror row_mask:0xf bank_mask:0xf bound_ctrl:1
	s_nop 1
	v_add_f32_dpp v18, v18, v18 row_mirror row_mask:0xf bank_mask:0xf bound_ctrl:1
	v_mov_b32_e32 v19, v18
	s_nop 1
	v_permlane16_swap_b32_e32 v18, v19
	v_add_f32_e32 v18, v18, v19
	v_mov_b32_e32 v19, v18
	s_nop 1
	v_permlane32_swap_b32_e32 v18, v19
	v_add_f32_e32 v18, v18, v19
	v_fmamk_f32 v18, v18, 0x3a000000, v66
	v_mul_f32_e32 v19, 0x4b800000, v18
	v_cmp_gt_f32_e32 vcc, s17, v18
	s_nop 1
	v_cndmask_b32_e32 v18, v18, v19, vcc
	v_rsq_f32_e32 v18, v18
	s_nop 0
	v_mul_f32_e32 v19, 0x45800000, v18
	v_cndmask_b32_e32 v58, v18, v19, vcc
	v_pk_mul_f32 v[18:19], v[34:35], v[58:59] op_sel_hi:[1,0]
	v_pk_mul_f32 v[20:21], v[32:33], v[58:59] op_sel_hi:[1,0]
	s_nop 0
	v_pk_mul_f32 v[18:19], v[28:29], v[18:19]
	v_pk_mul_f32 v[20:21], v[30:31], v[20:21]
	global_store_dwordx4 v[60:61], v[18:21], off
	s_nop 1
	v_mov_b64_e32 v[18:19], v[124:125]
	v_mov_b64_e32 v[20:21], v[126:127]
	v_pk_mul_f32 v[28:29], v[38:39], v[58:59] op_sel_hi:[1,0]
	v_pk_mul_f32 v[30:31], v[36:37], v[58:59] op_sel_hi:[1,0]
	v_pk_mul_f32 v[26:27], v[26:27], v[58:59] op_sel_hi:[1,0]
	v_pk_mul_f32 v[24:25], v[24:25], v[58:59] op_sel_hi:[1,0]
	v_pk_mul_f32 v[22:23], v[22:23], v[58:59] op_sel_hi:[1,0]
	s_nop 0
	v_pk_mul_f32 v[18:19], v[18:19], v[30:31]
	v_pk_mul_f32 v[20:21], v[20:21], v[28:29]
	global_store_dwordx4 v[60:61], v[18:21], off offset:1024
	s_nop 1
	v_mov_b64_e32 v[18:19], v[128:129]
	v_mov_b64_e32 v[20:21], v[130:131]
	v_pk_mul_f32 v[28:29], v[42:43], v[58:59] op_sel_hi:[1,0]
	v_pk_mul_f32 v[30:31], v[40:41], v[58:59] op_sel_hi:[1,0]
	s_nop 0
	v_pk_mul_f32 v[20:21], v[20:21], v[28:29]
	v_pk_mul_f32 v[18:19], v[18:19], v[30:31]
	global_store_dwordx4 v[60:61], v[18:21], off offset:2048
	s_nop 1
	v_mov_b64_e32 v[18:19], v[132:133]
	v_mov_b64_e32 v[20:21], v[134:135]
	v_pk_mul_f32 v[28:29], v[46:47], v[58:59] op_sel_hi:[1,0]
	v_pk_mul_f32 v[30:31], v[44:45], v[58:59] op_sel_hi:[1,0]
	s_nop 0
	v_pk_mul_f32 v[20:21], v[20:21], v[28:29]
	v_pk_mul_f32 v[18:19], v[18:19], v[30:31]
	global_store_dwordx4 v[60:61], v[18:21], off offset:3072
	s_nop 1
	v_mov_b64_e32 v[18:19], v[136:137]
	v_mov_b64_e32 v[20:21], v[138:139]
	v_add_co_u32_e32 v28, vcc, s18, v60
	v_pk_mul_f32 v[30:31], v[48:49], v[58:59] op_sel_hi:[1,0]
	s_nop 0
	v_addc_co_u32_e32 v29, vcc, 0, v61, vcc
	s_nop 0
	v_pk_mul_f32 v[18:19], v[18:19], v[30:31]
	v_pk_mul_f32 v[20:21], v[20:21], v[26:27]
	global_store_dwordx4 v[28:29], v[18:21], off
	s_nop 1
	v_mov_b64_e32 v[18:19], v[140:141]
	v_mov_b64_e32 v[20:21], v[142:143]
	v_pk_mul_f32 v[26:27], v[50:51], v[58:59] op_sel_hi:[1,0]
	s_nop 0
	v_pk_mul_f32 v[20:21], v[20:21], v[24:25]
	v_pk_mul_f32 v[18:19], v[18:19], v[26:27]
	global_store_dwordx4 v[28:29], v[18:21], off offset:1024
	s_nop 1
	v_mov_b64_e32 v[18:19], v[144:145]
	v_mov_b64_e32 v[20:21], v[146:147]
	v_pk_mul_f32 v[24:25], v[52:53], v[58:59] op_sel_hi:[1,0]
	s_nop 0
	v_pk_mul_f32 v[20:21], v[22:23], v[20:21]
	v_pk_mul_f32 v[18:19], v[24:25], v[18:19]
	global_store_dwordx4 v[28:29], v[18:21], off offset:2048
	s_nop 1
	v_mov_b64_e32 v[18:19], v[148:149]
	v_mov_b64_e32 v[20:21], v[150:151]
	v_pk_mul_f32 v[22:23], v[56:57], v[58:59] op_sel_hi:[1,0]
	v_pk_mul_f32 v[24:25], v[54:55], v[58:59] op_sel_hi:[1,0]
	s_nop 0
	v_pk_mul_f32 v[20:21], v[22:23], v[20:21]
	v_pk_mul_f32 v[18:19], v[24:25], v[18:19]
	global_store_dwordx4 v[28:29], v[18:21], off offset:3072
	s_branch .LBB0_3063
